# rnn pass 2 prefetch guarded on grid-half size multiple of 16 (robustness); otherwise same as previous best
# speedup vs baseline: 1.0371x; 1.0004x over previous
; DI void rnn_phase(LAS unsigned char* lds, bf16_t* P, const bf16_t* WaT, const bf16_t* WiT, const float* convw, const float* convb, const float* ba, const float* bi, const float* lam,
;                   f32x2* sums, unsigned* au, bool fin, int bx, int G, int tid, int wid, int lane) {
;     ...
;         for (int u2 = bx; u2 < NU; u2 += G) {
;             const int hbk = u2 & 15, c = (u2 >> 4) & 63, b = u2 >> 10;
;             const size_t rowbase = (size_t)b * SEQ + c * 128; const int ch0 = hbk * 64, ch = lane, seg = wid;
;             const unsigned* aup = au + (rowbase + 16 * seg) * D + ch0 + ch;
;             bf16_t* yp = P + (rowbase + 16 * seg) * DIN + PC_Y + ch0 + ch;
;             unsigned w[16]; unsigned short yv[16];
; #pragma unroll
;             for (int j = 0; j < 16; ++j) { w[j] = aup[(size_t)j * D]; yv[j] = yp[(size_t)j * DIN]; }
.LBB0_380:
	s_waitcnt vmcnt(0) lgkmcnt(0)
	s_and_b32 s25, s29, 15
	s_cmp_lg_u32 s25, 0
	s_cbranch_scc1 .Lr2_nopf
	s_add_i32 s25, s1, s29
	s_cmpk_gt_i32 s25, 0x7ff
	s_cbranch_scc1 .Lr2_nopf
	s_lshl_b32 s25, s29, 15
	s_add_u32 s22, s74, s25
	s_addc_u32 s23, s75, 0
	s_mul_i32 s25, s29, 0x1e000
	s_add_u32 s38, s72, s25
	s_addc_u32 s39, s73, 0
	v_lshlrev_b32_e32 v125, 2, v64
	v_lshlrev_b32_e32 v126, 1, v64
	v_add_u32_e32 v124, 0x0, v125
	global_load_dword v176, v124, s[22:23]
	v_add_u32_e32 v124, 0x1000, v125
	global_load_dword v177, v124, s[22:23]
	v_add_u32_e32 v124, 0x2000, v125
	global_load_dword v178, v124, s[22:23]
	v_add_u32_e32 v124, 0x3000, v125
	global_load_dword v179, v124, s[22:23]
	v_add_u32_e32 v124, 0x4000, v125
	global_load_dword v180, v124, s[22:23]
	v_add_u32_e32 v124, 0x5000, v125
	global_load_dword v181, v124, s[22:23]
	v_add_u32_e32 v124, 0x6000, v125
	global_load_dword v182, v124, s[22:23]
	v_add_u32_e32 v124, 0x7000, v125
	global_load_dword v183, v124, s[22:23]
	v_add_u32_e32 v124, 0x8000, v125
	global_load_dword v184, v124, s[22:23]
	v_add_u32_e32 v124, 0x9000, v125
	global_load_dword v185, v124, s[22:23]
	v_add_u32_e32 v124, 0xa000, v125
	global_load_dword v186, v124, s[22:23]
	v_add_u32_e32 v124, 0xb000, v125
	global_load_dword v187, v124, s[22:23]
	v_add_u32_e32 v124, 0xc000, v125
	global_load_dword v188, v124, s[22:23]
	v_add_u32_e32 v124, 0xd000, v125
	global_load_dword v189, v124, s[22:23]
	v_add_u32_e32 v124, 0xe000, v125
	global_load_dword v190, v124, s[22:23]
	v_add_u32_e32 v124, 0xf000, v125
	global_load_dword v191, v124, s[22:23]
	v_add_u32_e32 v124, 0x800, v126
	global_load_ushort v192, v124, s[38:39]
	v_add_u32_e32 v124, 0x4400, v126
	global_load_ushort v193, v124, s[38:39]
	v_add_u32_e32 v124, 0x8000, v126
	global_load_ushort v194, v124, s[38:39]
	v_add_u32_e32 v124, 0xbc00, v126
	global_load_ushort v195, v124, s[38:39]
	v_add_u32_e32 v124, 0xf800, v126
	global_load_ushort v196, v124, s[38:39]
	v_add_u32_e32 v124, 0x13400, v126
	global_load_ushort v197, v124, s[38:39]
	v_add_u32_e32 v124, 0x17000, v126
	global_load_ushort v198, v124, s[38:39]
	v_add_u32_e32 v124, 0x1ac00, v126
	global_load_ushort v199, v124, s[38:39]
	v_add_u32_e32 v124, 0x1e800, v126
	global_load_ushort v200, v124, s[38:39]
	v_add_u32_e32 v124, 0x22400, v126
	global_load_ushort v201, v124, s[38:39]
	v_add_u32_e32 v124, 0x26000, v126
	global_load_ushort v202, v124, s[38:39]
	v_add_u32_e32 v124, 0x29c00, v126
	global_load_ushort v203, v124, s[38:39]
	v_add_u32_e32 v124, 0x2d800, v126
	global_load_ushort v204, v124, s[38:39]
	v_add_u32_e32 v124, 0x31400, v126
	global_load_ushort v205, v124, s[38:39]
	v_add_u32_e32 v124, 0x35000, v126
	global_load_ushort v206, v124, s[38:39]
	v_add_u32_e32 v124, 0x38c00, v126
	global_load_ushort v207, v124, s[38:39]
	s_mov_b32 s25, 1
	s_branch .Lr2_pfset
